# prologue weight transposes: the 8 RMSNorm-gain loads of an item issued together with its tile loads (were 4 serialized round trips)
# speedup vs baseline: 1.0116x; 1.0116x over previous
; #define LAS __attribute__((address_space(3)))
; #define LDS_WAIT() asm volatile("s_waitcnt lgkmcnt(0)" ::: "memory")
; __device__ __forceinline__ void transpose_item(const float* W, int K, int N, bf16_t* WT, int mode, const float* kscale, LAS float* scr, int item, int lane) {
;     const int nblk = N / 32, kb = item / nblk, nb = item % nblk, k0 = 64 * kb, n0 = 32 * nb;
;     const int drow = (mode == 0 || mode == 3) ? n0 : ((n0 >> 7) * 256 + (n0 & 127) + (mode == 2 ? 128 : 0));
;     f32x4 t[8];
; #pragma unroll
;     for (int i = 0; i < 8; ++i) t[i] = *(const f32x4*)(W + (size_t)(k0 + 8 * i + (lane >> 3)) * N + n0 + 4 * (lane & 7));
; #pragma unroll
;     for (int i = 0; i < 8; ++i) { const int kk = 8 * i + (lane >> 3); const float sc = kscale ? kscale[k0 + kk] : 1.f; LAS float* d = scr + kk * 33 + 4 * (lane & 7);
;         d[0] = t[i][0] * sc; d[1] = t[i][1] * sc; d[2] = t[i][2] * sc; d[3] = t[i][3] * sc; }
;     LDS_WAIT(); asm volatile("" ::: "memory");
.LBB0_526:
	s_andn2_b64 vcc, exec, s[6:7]
	s_cbranch_vccnz .LBB0_536
	s_load_dwordx2 s[6:7], s[16:17], 0x70
	s_load_dwordx2 s[34:35], s[16:17], 0x60
	v_lshlrev_b32_e32 v196, 2, v36
	v_mov_b32_e32 v40, 1.0
	v_mov_b32_e32 v42, 1.0
	s_waitcnt lgkmcnt(0)
	s_add_u32 s10, s6, s21
	s_addc_u32 s11, s7, s20
	s_lshl_b64 s[6:7], s[18:19], 13
	s_add_u32 s8, s34, s6
	s_addc_u32 s9, s35, s7
	s_add_i32 s6, s22, 0xc600
	s_and_b32 s7, s6, 0xffff
	s_mul_i32 s7, s7, 0xba2f
	s_lshr_b32 s7, s7, 23
	s_mul_i32 s30, s7, 0xb0
	s_sub_i32 s6, s6, s30
	s_and_b32 s30, s6, 0xffff
	s_lshl_b32 s23, s7, 6
	s_lshl_b32 s6, s30, 7
	s_add_u32 s6, s10, s6
	v_or_b32_e32 v44, s23, v34
	s_addc_u32 s7, s11, 0
	v_lshl_add_u64 v[2:3], s[6:7], 0, v[196:197]
	s_movk_i32 s6, 0x5800
	v_mul_u32_u24_e32 v6, 0x1600, v44
	v_mad_u64_u32 v[4:5], s[6:7], v44, s6, v[2:3]
	v_lshlrev_b32_e32 v196, 2, v6
	v_lshl_add_u64 v[2:3], v[2:3], 0, v[196:197]
	s_mov_b32 s6, 0x2c000
	v_add_co_u32_e32 v6, vcc, s6, v2
	s_mov_b32 s6, 0x58000
	s_nop 0
	v_addc_co_u32_e32 v7, vcc, 0, v3, vcc
	global_load_dwordx4 v[30:33], v[4:5], off
	global_load_dwordx4 v[26:29], v[6:7], off
	v_add_co_u32_e32 v4, vcc, s6, v2
	s_mov_b32 s6, 0x84000
	s_nop 0
	v_addc_co_u32_e32 v5, vcc, 0, v3, vcc
	v_add_co_u32_e32 v6, vcc, s6, v2
	s_mov_b32 s6, 0xb0000
	s_nop 0
	v_addc_co_u32_e32 v7, vcc, 0, v3, vcc
	global_load_dwordx4 v[22:25], v[4:5], off
	global_load_dwordx4 v[18:21], v[6:7], off
	v_add_co_u32_e32 v4, vcc, s6, v2
	s_mov_b32 s6, 0xdc000
	s_nop 0
	v_addc_co_u32_e32 v5, vcc, 0, v3, vcc
	v_add_co_u32_e32 v6, vcc, s6, v2
	s_cmp_lg_u64 s[34:35], 0
	s_nop 0
	v_addc_co_u32_e32 v7, vcc, 0, v3, vcc
	global_load_dwordx4 v[14:17], v[4:5], off
	global_load_dwordx4 v[10:13], v[6:7], off
	v_add_co_u32_e32 v4, vcc, 0x108000, v2
	s_cselect_b64 s[10:11], -1, 0
	s_nop 0
	v_addc_co_u32_e32 v5, vcc, 0, v3, vcc
	v_add_co_u32_e32 v2, vcc, 0x134000, v2
	s_cmp_eq_u64 s[34:35], 0
	s_nop 0
	v_addc_co_u32_e32 v3, vcc, 0, v3, vcc
	global_load_dwordx4 v[6:9], v[4:5], off
	s_nop 0
	global_load_dwordx4 v[2:5], v[2:3], off
	v_add_lshl_u32 v43, v34, s23, 2
	s_cbranch_scc1 .LBB0_529
	v_lshlrev_b32_e32 v42, 2, v44
	global_load_dword v44, v42, s[8:9]
	s_nop 0
	global_load_dword v42, v43, s[8:9] offset:32
	global_load_dword v100, v43, s[8:9] offset:64
	global_load_dword v101, v43, s[8:9] offset:96
	global_load_dword v102, v43, s[8:9] offset:128
	global_load_dword v103, v43, s[8:9] offset:160
	global_load_dword v104, v43, s[8:9] offset:192
	global_load_dword v105, v43, s[8:9] offset:224
	s_waitcnt vmcnt(0)
	v_pk_mul_f32 v[30:31], v[30:31], v[44:45] op_sel_hi:[1,0]
	v_pk_mul_f32 v[32:33], v[32:33], v[44:45] op_sel_hi:[1,0]
.LBB0_529:
	v_add_u32_e32 v44, v39, v41
	s_waitcnt vmcnt(0)
	ds_write2_b32 v44, v30, v31 offset1:1
	ds_write2_b32 v44, v32, v33 offset0:2 offset1:3
	v_pk_mul_f32 v[26:27], v[26:27], v[42:43] op_sel_hi:[1,0]
	v_add_u32_e32 v30, 0x420, v44
	ds_write2_b32 v30, v26, v27 offset1:1
	v_pk_mul_f32 v[26:27], v[28:29], v[42:43] op_sel_hi:[1,0]
	v_cndmask_b32_e64 v29, 0, 1, s[10:11]
	v_add_u32_e32 v28, 0x428, v44
	v_cmp_ne_u32_e64 s[6:7], 1, v29
	s_andn2_b64 vcc, exec, s[10:11]
	ds_write2_b32 v28, v26, v27 offset1:1
	s_cbranch_vccnz .LBB0_531
	v_mov_b32_e32 v26, v100
	v_mov_b32_e32 v40, v101
	s_waitcnt vmcnt(1)
	v_pk_mul_f32 v[22:23], v[22:23], v[26:27] op_sel_hi:[1,0]
	v_pk_mul_f32 v[24:25], v[24:25], v[26:27] op_sel_hi:[1,0]
.LBB0_531:
	v_add_u32_e32 v26, 0x840, v44
	ds_write2_b32 v26, v22, v23 offset1:1
	v_add_u32_e32 v22, 0x848, v44
	ds_write2_b32 v22, v24, v25 offset1:1
	s_waitcnt vmcnt(0)
	v_pk_mul_f32 v[18:19], v[18:19], v[40:41] op_sel_hi:[1,0]
	v_add_u32_e32 v22, 0xc60, v44
	ds_write2_b32 v22, v18, v19 offset1:1
	v_pk_mul_f32 v[18:19], v[20:21], v[40:41] op_sel_hi:[1,0]
	v_add_u32_e32 v20, 0xc68, v44
	ds_write2_b32 v20, v18, v19 offset1:1
	v_mov_b32_e32 v18, 1.0
	s_and_b64 vcc, exec, s[6:7]
	v_mov_b32_e32 v20, 1.0
	s_cbranch_vccnz .LBB0_533
	v_mov_b32_e32 v22, v102
	v_mov_b32_e32 v20, v103
	s_waitcnt vmcnt(1)
	v_pk_mul_f32 v[14:15], v[14:15], v[22:23] op_sel_hi:[1,0]
	v_pk_mul_f32 v[16:17], v[16:17], v[22:23] op_sel_hi:[1,0]
.LBB0_533:
	v_add_u32_e32 v19, v39, v49
	ds_write2_b32 v19, v14, v15 offset1:1
	ds_write2_b32 v19, v16, v17 offset0:2 offset1:3
	s_waitcnt vmcnt(0)
	v_pk_mul_f32 v[10:11], v[10:11], v[20:21] op_sel_hi:[1,0]
	v_add_u32_e32 v14, 0x420, v19
	ds_write2_b32 v14, v10, v11 offset1:1
	v_pk_mul_f32 v[10:11], v[12:13], v[20:21] op_sel_hi:[1,0]
	v_add_u32_e32 v12, 0x428, v19
	s_and_b64 vcc, exec, s[6:7]
	ds_write2_b32 v12, v10, v11 offset1:1
	s_cbranch_vccnz .LBB0_535
	v_mov_b32_e32 v10, v104
	v_mov_b32_e32 v18, v105
	s_waitcnt vmcnt(1)
	v_pk_mul_f32 v[6:7], v[6:7], v[10:11] op_sel_hi:[1,0]
	v_pk_mul_f32 v[8:9], v[8:9], v[10:11] op_sel_hi:[1,0]

; #define LAS __attribute__((address_space(3)))
; __device__ __forceinline__ void transpose_item(const float* W, int K, int N, bf16_t* WT, int mode, const float* kscale, LAS float* scr, int item, int lane) {
;     const int nblk = N / 32, kb = item / nblk, nb = item % nblk, k0 = 64 * kb, n0 = 32 * nb;
;     const int drow = (mode == 0 || mode == 3) ? n0 : ((n0 >> 7) * 256 + (n0 & 127) + (mode == 2 ? 128 : 0));
;     f32x4 t[8];
; #pragma unroll
;     for (int i = 0; i < 8; ++i) t[i] = *(const f32x4*)(W + (size_t)(k0 + 8 * i + (lane >> 3)) * N + n0 + 4 * (lane & 7));
; #pragma unroll
;     for (int i = 0; i < 8; ++i) { const int kk = 8 * i + (lane >> 3); const float sc = kscale ? kscale[k0 + kk] : 1.f; LAS float* d = scr + kk * 33 + 4 * (lane & 7);
;         d[0] = t[i][0] * sc; d[1] = t[i][1] * sc; d[2] = t[i][2] * sc; d[3] = t[i][3] * sc; }
.LBB0_537:
	s_andn2_b64 vcc, exec, s[6:7]
	s_cbranch_vccnz .LBB0_547
	s_load_dwordx4 s[8:11], s[16:17], 0x60
	v_lshlrev_b32_e32 v196, 2, v36
	v_mov_b32_e32 v40, 1.0
	v_mov_b32_e32 v42, 1.0
	s_waitcnt lgkmcnt(0)
	s_add_u32 s21, s10, s21
	s_addc_u32 s20, s11, s20
	s_lshl_b64 s[6:7], s[18:19], 13
	s_add_u32 s10, s8, s6
	s_addc_u32 s11, s9, s7
	s_add_i32 s6, s22, 0xdc00
	s_and_b32 s7, s6, 0xffff
	s_mul_i32 s7, s7, 0xba2f
	s_lshr_b32 s7, s7, 23
	s_mul_i32 s30, s7, 0xb0
	s_sub_i32 s6, s6, s30
	s_and_b32 s30, s6, 0xffff
	s_lshl_b32 s23, s7, 6
	s_lshl_b32 s6, s30, 7
	s_add_u32 s6, s21, s6
	v_or_b32_e32 v44, s23, v34
	s_addc_u32 s7, s20, 0
	v_lshl_add_u64 v[2:3], s[6:7], 0, v[196:197]
	s_movk_i32 s6, 0x5800
	v_mul_u32_u24_e32 v6, 0x1600, v44
	v_mad_u64_u32 v[4:5], s[6:7], v44, s6, v[2:3]
	v_lshlrev_b32_e32 v196, 2, v6
	v_lshl_add_u64 v[2:3], v[2:3], 0, v[196:197]
	s_mov_b32 s6, 0x2c000
	v_add_co_u32_e32 v6, vcc, s6, v2
	s_mov_b32 s6, 0x58000
	s_nop 0
	v_addc_co_u32_e32 v7, vcc, 0, v3, vcc
	global_load_dwordx4 v[30:33], v[4:5], off
	global_load_dwordx4 v[26:29], v[6:7], off
	v_add_co_u32_e32 v4, vcc, s6, v2
	s_mov_b32 s6, 0x84000
	s_nop 0
	v_addc_co_u32_e32 v5, vcc, 0, v3, vcc
	v_add_co_u32_e32 v6, vcc, s6, v2
	s_mov_b32 s6, 0xb0000
	s_nop 0
	v_addc_co_u32_e32 v7, vcc, 0, v3, vcc
	global_load_dwordx4 v[22:25], v[4:5], off
	global_load_dwordx4 v[18:21], v[6:7], off
	v_add_co_u32_e32 v4, vcc, s6, v2
	s_mov_b32 s6, 0xdc000
	s_nop 0
	v_addc_co_u32_e32 v5, vcc, 0, v3, vcc
	v_add_co_u32_e32 v6, vcc, s6, v2
	s_cmp_lg_u64 s[8:9], 0
	s_nop 0
	v_addc_co_u32_e32 v7, vcc, 0, v3, vcc
	global_load_dwordx4 v[14:17], v[4:5], off
	global_load_dwordx4 v[10:13], v[6:7], off
	v_add_co_u32_e32 v4, vcc, 0x108000, v2
	s_cselect_b64 s[20:21], -1, 0
	s_nop 0
	v_addc_co_u32_e32 v5, vcc, 0, v3, vcc
	v_add_co_u32_e32 v2, vcc, 0x134000, v2
	s_cmp_eq_u64 s[8:9], 0
	s_nop 0
	v_addc_co_u32_e32 v3, vcc, 0, v3, vcc
	global_load_dwordx4 v[6:9], v[4:5], off
	s_nop 0
	global_load_dwordx4 v[2:5], v[2:3], off
	v_add_lshl_u32 v43, v34, s23, 2
	s_cbranch_scc1 .LBB0_540
	v_lshlrev_b32_e32 v42, 2, v44
	global_load_dword v44, v42, s[10:11]
	s_nop 0
	global_load_dword v42, v43, s[10:11] offset:32
	global_load_dword v100, v43, s[10:11] offset:64
	global_load_dword v101, v43, s[10:11] offset:96
	global_load_dword v102, v43, s[10:11] offset:128
	global_load_dword v103, v43, s[10:11] offset:160
	global_load_dword v104, v43, s[10:11] offset:192
	global_load_dword v105, v43, s[10:11] offset:224
	s_waitcnt vmcnt(0)
	v_pk_mul_f32 v[30:31], v[30:31], v[44:45] op_sel_hi:[1,0]
	v_pk_mul_f32 v[32:33], v[32:33], v[44:45] op_sel_hi:[1,0]
.LBB0_540:
	v_add_u32_e32 v44, v39, v41
	s_waitcnt vmcnt(0)
	ds_write2_b32 v44, v30, v31 offset1:1
	ds_write2_b32 v44, v32, v33 offset0:2 offset1:3
	v_pk_mul_f32 v[26:27], v[26:27], v[42:43] op_sel_hi:[1,0]
	v_add_u32_e32 v30, 0x420, v44
	ds_write2_b32 v30, v26, v27 offset1:1
	v_pk_mul_f32 v[26:27], v[28:29], v[42:43] op_sel_hi:[1,0]
	v_cndmask_b32_e64 v29, 0, 1, s[20:21]
	v_add_u32_e32 v28, 0x428, v44
	v_cmp_ne_u32_e64 s[6:7], 1, v29
	s_andn2_b64 vcc, exec, s[20:21]
	ds_write2_b32 v28, v26, v27 offset1:1
	s_cbranch_vccnz .LBB0_542
	v_mov_b32_e32 v26, v100
	v_mov_b32_e32 v40, v101
	s_waitcnt vmcnt(1)
	v_pk_mul_f32 v[22:23], v[22:23], v[26:27] op_sel_hi:[1,0]
	v_pk_mul_f32 v[24:25], v[24:25], v[26:27] op_sel_hi:[1,0]
